# SGU: hoist v-block loads above the rsd round trip; barrier census loads issued together
# speedup vs baseline: 1.0245x; 1.0021x over previous
; #define LAS __attribute__((address_space(3)))
; __device__ __forceinline__ unsigned cvt_pk_bf16(float lo, float hi) { f32x2 v = {lo, hi}; bf16x2_t b = __builtin_convertvector(v, bf16x2_t); return __builtin_bit_cast(unsigned, b); }
; __device__ __forceinline__ float bf_lo(unsigned w) { return __uint_as_float(w << 16); }
; __device__ __forceinline__ float bf_hi(unsigned w) { return __uint_as_float(w & 0xffff0000u); }
; __device__ __forceinline__ void sgu_phase(KP kp, LAS unsigned char* lds, int l) {
;     ...
;         if (tid < 128) { float s = 0.f;
; #pragma unroll
;             for (int j = 0; j < 16; ++j) s += ssqv[(size_t)j * M + r0 + tid];
;             rsd[tid] = __builtin_amdgcn_rsqf(s * (1.0f / 1024.0f) + EPS); }
;         __syncthreads();
;         { const int dc = tid & 15; const f32x4 g0 = *(const f32x4*)(gn + h * 128 + dc * 8), g1 = *(const f32x4*)(gn + h * 128 + dc * 8 + 4);
; #pragma unroll
;           for (int j = 0; j < 4; ++j) { const int s = (tid >> 4) + 32 * j; const u32x4 raw = *(const u32x4*)(Z + (size_t)(r0 + s) * NIN + 2048 + h * 128 + dc * 8); const float r = rsd[s];
;               u32x4 wv; wv.x = cvt_pk_bf16(bf_lo(raw.x) * r * g0.x, bf_hi(raw.x) * r * g0.y); wv.y = cvt_pk_bf16(bf_lo(raw.y) * r * g0.z, bf_hi(raw.y) * r * g0.w);
;               wv.z = cvt_pk_bf16(bf_lo(raw.z) * r * g1.x, bf_hi(raw.z) * r * g1.y); wv.w = cvt_pk_bf16(bf_lo(raw.w) * r * g1.z, bf_hi(raw.w) * r * g1.w);
;               *(LAS u32x4*)(lds + 256 * s + 16 * (dc ^ (((s & 3) << 2) | ((s >> 2) & 3)))) = wv; } }
.LBB0_80:
	s_lshl_b32 s12, s2, 4
	s_and_b32 s12, s12, 0xffffff80
	s_and_b32 s2, s2, 7
	s_lshl_b32 s30, s2, 9
	v_add_u32_e32 v2, s12, v134
	v_mov_b64_e32 v[22:23], s[70:71]
	v_lshl_add_u64 v[14:15], v[104:105], 0, s[30:31]
	v_mad_i64_i32 v[2:3], s[16:17], v2, s69, v[22:23]
	s_lshl_b32 s30, s2, 8
	v_lshl_add_u64 v[2:3], v[2:3], 0, s[30:31]
	v_add_u32_e32 v6, s12, v138
	v_lshl_add_u64 v[2:3], v[2:3], 0, v[0:1]
	s_movk_i32 s13, 0x1000
	v_mad_i64_i32 v[6:7], s[16:17], v6, s69, v[22:23]
	v_add_co_u32_e32 v2, vcc, s13, v2
	v_lshl_add_u64 v[6:7], v[6:7], 0, s[30:31]
	s_nop 0
	v_addc_co_u32_e32 v3, vcc, 0, v3, vcc
	v_lshl_add_u64 v[6:7], v[6:7], 0, v[0:1]
	global_load_dwordx4 v[2:5], v[2:3], off
	v_add_co_u32_e32 v6, vcc, s13, v6
	v_add_u32_e32 v18, s12, v139
	s_nop 0
	v_addc_co_u32_e32 v7, vcc, 0, v7, vcc
	global_load_dwordx4 v[6:9], v[6:7], off
	s_nop 0
	global_load_dwordx4 v[10:13], v[14:15], off
	s_nop 0
	global_load_dwordx4 v[14:17], v[14:15], off offset:16
	v_mad_i64_i32 v[18:19], s[16:17], v18, s69, v[22:23]
	v_lshl_add_u64 v[18:19], v[18:19], 0, s[30:31]
	v_lshl_add_u64 v[18:19], v[18:19], 0, v[0:1]
	v_add_co_u32_e32 v18, vcc, s13, v18
	v_add_u32_e32 v24, s12, v140
	s_nop 0
	v_addc_co_u32_e32 v19, vcc, 0, v19, vcc
	global_load_dwordx4 v[18:21], v[18:19], off
	v_mad_i64_i32 v[22:23], s[16:17], v24, s69, v[22:23]
	v_lshl_add_u64 v[22:23], v[22:23], 0, s[30:31]
	v_lshl_add_u64 v[22:23], v[22:23], 0, v[0:1]
	v_add_co_u32_e32 v22, vcc, s13, v22
	s_nop 1
	v_addc_co_u32_e32 v23, vcc, 0, v23, vcc
	global_load_dwordx4 v[22:25], v[22:23], off
	s_and_saveexec_b64 s[16:17], s[40:41]
	s_cbranch_execz .LBB0_82
	s_ashr_i32 s13, s12, 31
	v_lshl_add_u64 v[166:167], s[12:13], 2, v[102:103]
	v_add_co_u32_e32 v168, vcc, 0x10000, v166
	s_mov_b32 s3, 0x50000
	s_nop 0
	v_addc_co_u32_e32 v169, vcc, 0, v167, vcc
	v_add_co_u32_e32 v170, vcc, 0x20000, v166
	s_mov_b32 s13, 0x60000
	s_nop 0
	v_addc_co_u32_e32 v171, vcc, 0, v167, vcc
	v_add_co_u32_e32 v172, vcc, 0x30000, v166
	s_nop 1
	v_addc_co_u32_e32 v173, vcc, 0, v167, vcc
	v_add_co_u32_e32 v174, vcc, 0x40000, v166
	s_nop 1
	v_addc_co_u32_e32 v175, vcc, 0, v167, vcc
	v_add_co_u32_e32 v176, vcc, s3, v166
	s_movk_i32 s3, 0x2000
	s_nop 0
	v_addc_co_u32_e32 v177, vcc, 0, v167, vcc
	v_add_co_u32_e32 v178, vcc, s13, v166
	s_nop 1
	v_addc_co_u32_e32 v179, vcc, 0, v167, vcc
	v_add_co_u32_e32 v180, vcc, 0x70000, v166
	s_nop 1
	v_addc_co_u32_e32 v181, vcc, 0, v167, vcc
	global_load_dword v182, v[166:167], off
	global_load_dword v183, v[168:169], off
	global_load_dword v184, v[170:171], off
	global_load_dword v185, v[172:173], off
	global_load_dword v186, v[174:175], off
	global_load_dword v187, v[176:177], off
	global_load_dword v188, v[178:179], off
	global_load_dword v189, v[180:181], off
	v_add_co_u32_e32 v168, vcc, 0x80000, v166
	s_nop 1
	v_addc_co_u32_e32 v169, vcc, 0, v167, vcc
	v_add_co_u32_e32 v170, vcc, 0x90000, v166
	s_nop 1
	v_addc_co_u32_e32 v171, vcc, 0, v167, vcc
	v_add_co_u32_e32 v172, vcc, 0xa0000, v166
	s_nop 1
	v_addc_co_u32_e32 v173, vcc, 0, v167, vcc
	v_add_co_u32_e32 v174, vcc, 0xb0000, v166
	s_nop 1
	v_addc_co_u32_e32 v175, vcc, 0, v167, vcc
	v_add_co_u32_e32 v176, vcc, 0xc0000, v166
	s_nop 1
	v_addc_co_u32_e32 v177, vcc, 0, v167, vcc
	v_add_co_u32_e32 v178, vcc, 0xd0000, v166
	s_nop 1
	v_addc_co_u32_e32 v179, vcc, 0, v167, vcc
	v_add_co_u32_e32 v180, vcc, 0xe0000, v166
	s_nop 1
	v_addc_co_u32_e32 v181, vcc, 0, v167, vcc
	v_add_co_u32_e32 v166, vcc, 0xf0000, v166
	s_nop 1
	v_addc_co_u32_e32 v167, vcc, 0, v167, vcc
	global_load_dword v168, v[168:169], off
	s_nop 0
	global_load_dword v169, v[170:171], off
	s_nop 0
	global_load_dword v170, v[172:173], off
	global_load_dword v171, v[174:175], off
	s_nop 0
	global_load_dword v172, v[176:177], off
	global_load_dword v173, v[178:179], off
	global_load_dword v174, v[180:181], off
	s_nop 0
	global_load_dword v166, v[166:167], off
	s_waitcnt vmcnt(0)
	v_add_f32_e32 v167, 0, v182
	s_waitcnt vmcnt(14)
	v_add_f32_e32 v167, v167, v183
	s_waitcnt vmcnt(13)
	v_add_f32_e32 v167, v167, v184
	s_waitcnt vmcnt(12)
	v_add_f32_e32 v167, v167, v185
	s_waitcnt vmcnt(11)
	v_add_f32_e32 v167, v167, v186
	s_waitcnt vmcnt(10)
	v_add_f32_e32 v167, v167, v187
	s_waitcnt vmcnt(9)
	v_add_f32_e32 v167, v167, v188
	s_waitcnt vmcnt(8)
	v_add_f32_e32 v167, v167, v189
	s_waitcnt vmcnt(7)
	v_add_f32_e32 v167, v167, v168
	s_waitcnt vmcnt(6)
	v_add_f32_e32 v167, v167, v169
	s_waitcnt vmcnt(5)
	v_add_f32_e32 v167, v167, v170
	s_waitcnt vmcnt(4)
	v_add_f32_e32 v167, v167, v171
	s_waitcnt vmcnt(3)
	v_add_f32_e32 v167, v167, v172
	s_waitcnt vmcnt(2)
	v_add_f32_e32 v167, v167, v173
	s_waitcnt vmcnt(1)
	v_add_f32_e32 v167, v167, v174
	s_waitcnt vmcnt(0)
	v_add_f32_e32 v166, v167, v166
	v_fmamk_f32 v166, v166, 0x3a800000, v197
	v_rsq_f32_e32 v166, v166
	ds_write_b32 v111, v166 offset:40960
; #define LAS __attribute__((address_space(3)))
; __device__ __forceinline__ unsigned cvt_pk_bf16(float lo, float hi) { f32x2 v = {lo, hi}; bf16x2_t b = __builtin_convertvector(v, bf16x2_t); return __builtin_bit_cast(unsigned, b); }
; __device__ __forceinline__ float bf_lo(unsigned w) { return __uint_as_float(w << 16); }
; __device__ __forceinline__ float bf_hi(unsigned w) { return __uint_as_float(w & 0xffff0000u); }
; __device__ __forceinline__ void sgu_phase(KP kp, LAS unsigned char* lds, int l) {
;     ...
;         __syncthreads();
;         { const int dc = tid & 15; const f32x4 g0 = *(const f32x4*)(gn + h * 128 + dc * 8), g1 = *(const f32x4*)(gn + h * 128 + dc * 8 + 4);
; #pragma unroll
;           for (int j = 0; j < 4; ++j) { const int s = (tid >> 4) + 32 * j; const u32x4 raw = *(const u32x4*)(Z + (size_t)(r0 + s) * NIN + 2048 + h * 128 + dc * 8); const float r = rsd[s];
;               u32x4 wv; wv.x = cvt_pk_bf16(bf_lo(raw.x) * r * g0.x, bf_hi(raw.x) * r * g0.y); wv.y = cvt_pk_bf16(bf_lo(raw.y) * r * g0.z, bf_hi(raw.y) * r * g0.w);
;               wv.z = cvt_pk_bf16(bf_lo(raw.z) * r * g1.x, bf_hi(raw.z) * r * g1.y); wv.w = cvt_pk_bf16(bf_lo(raw.w) * r * g1.z, bf_hi(raw.w) * r * g1.w);
;               *(LAS u32x4*)(lds + 256 * s + 16 * (dc ^ (((s & 3) << 2) | ((s >> 2) & 3)))) = wv; } }
;         __syncthreads();
;         const int kkmax = (16 * wid + 15) >> 5;
;         bf16x8 wfa[4];
; #pragma unroll
;         for (int kk = 0; kk < 4; ++kk) wfa[kk] = (kk <= kkmax) ? *(const bf16x8*)(ws16 + (size_t)(h * 128 + 16 * wid + fr) * 128 + 32 * kk + 8 * fq) : (bf16x8){0, 0, 0, 0, 0, 0, 0, 0};
.LBB0_82:
	s_or_b64 exec, exec, s[16:17]
	s_waitcnt lgkmcnt(0)
	s_barrier
	ds_read_b32 v26, v137 offset:40960
	s_lshl_b32 s13, s2, 7
	s_waitcnt vmcnt(0)
	v_lshlrev_b32_e32 v28, 16, v2
	v_and_b32_e32 v29, 0xffff0000, v2
	v_lshlrev_b32_e32 v2, 16, v3
	v_and_b32_e32 v3, 0xffff0000, v3
	v_lshlrev_b32_e32 v30, 16, v4
	v_and_b32_e32 v31, 0xffff0000, v4
	v_lshlrev_b32_e32 v4, 16, v5
	v_and_b32_e32 v5, 0xffff0000, v5
	s_waitcnt lgkmcnt(0)
	v_pk_mul_f32 v[28:29], v[26:27], v[28:29] op_sel_hi:[0,1]
	v_pk_mul_f32 v[2:3], v[26:27], v[2:3] op_sel_hi:[0,1]
	v_pk_mul_f32 v[30:31], v[26:27], v[30:31] op_sel_hi:[0,1]
	v_pk_mul_f32 v[4:5], v[26:27], v[4:5] op_sel_hi:[0,1]
	s_waitcnt vmcnt(3)
	v_pk_mul_f32 v[26:27], v[10:11], v[28:29]
	v_pk_mul_f32 v[28:29], v[12:13], v[2:3]
	s_waitcnt vmcnt(2)
	v_pk_mul_f32 v[30:31], v[14:15], v[30:31]
	v_pk_mul_f32 v[36:37], v[16:17], v[4:5]
	v_cvt_pk_bf16_f32 v2, v26, v27
	v_cvt_pk_bf16_f32 v3, v28, v29
	v_cvt_pk_bf16_f32 v4, v30, v31
	v_cvt_pk_bf16_f32 v5, v36, v37
	ds_write_b128 v141, v[2:5]
	ds_read_b32 v2, v137 offset:41088
	v_lshlrev_b32_e32 v32, 16, v6
	v_and_b32_e32 v33, 0xffff0000, v6
	v_lshlrev_b32_e32 v6, 16, v7
	v_and_b32_e32 v7, 0xffff0000, v7
	v_lshlrev_b32_e32 v34, 16, v8
	v_and_b32_e32 v35, 0xffff0000, v8
	v_lshlrev_b32_e32 v4, 16, v9
	v_and_b32_e32 v5, 0xffff0000, v9
	s_waitcnt lgkmcnt(0)
	v_pk_mul_f32 v[26:27], v[2:3], v[32:33] op_sel_hi:[0,1]
	v_pk_mul_f32 v[6:7], v[2:3], v[6:7] op_sel_hi:[0,1]
	v_pk_mul_f32 v[28:29], v[2:3], v[34:35] op_sel_hi:[0,1]
	v_pk_mul_f32 v[2:3], v[2:3], v[4:5] op_sel_hi:[0,1]
	v_pk_mul_f32 v[4:5], v[10:11], v[26:27]
	v_pk_mul_f32 v[6:7], v[12:13], v[6:7]
	v_pk_mul_f32 v[26:27], v[14:15], v[28:29]
	v_pk_mul_f32 v[28:29], v[16:17], v[2:3]
	v_cvt_pk_bf16_f32 v2, v4, v5
	v_cvt_pk_bf16_f32 v3, v6, v7
	v_cvt_pk_bf16_f32 v4, v26, v27
	v_cvt_pk_bf16_f32 v5, v28, v29
	ds_write_b128 v142, v[2:5]
	ds_read_b32 v6, v137 offset:41216
	s_waitcnt vmcnt(1)
	v_lshlrev_b32_e32 v8, 16, v18
	v_and_b32_e32 v9, 0xffff0000, v18
	v_lshlrev_b32_e32 v2, 16, v19
	v_and_b32_e32 v3, 0xffff0000, v19
	s_waitcnt lgkmcnt(0)
	v_pk_mul_f32 v[8:9], v[6:7], v[8:9] op_sel_hi:[0,1]
	v_pk_mul_f32 v[2:3], v[6:7], v[2:3] op_sel_hi:[0,1]
	v_pk_mul_f32 v[8:9], v[10:11], v[8:9]
	v_lshlrev_b32_e32 v4, 16, v20
	v_and_b32_e32 v5, 0xffff0000, v20
	v_pk_mul_f32 v[18:19], v[12:13], v[2:3]
	v_cvt_pk_bf16_f32 v2, v8, v9
	v_lshlrev_b32_e32 v8, 16, v21
	v_and_b32_e32 v9, 0xffff0000, v21
	v_pk_mul_f32 v[4:5], v[6:7], v[4:5] op_sel_hi:[0,1]
	v_pk_mul_f32 v[6:7], v[6:7], v[8:9] op_sel_hi:[0,1]
	v_pk_mul_f32 v[4:5], v[14:15], v[4:5]
	v_pk_mul_f32 v[6:7], v[16:17], v[6:7]
	v_cvt_pk_bf16_f32 v3, v18, v19
	v_cvt_pk_bf16_f32 v4, v4, v5
	v_cvt_pk_bf16_f32 v5, v6, v7
	ds_write_b128 v143, v[2:5]
	ds_read_b32 v6, v137 offset:41344
	s_waitcnt vmcnt(0)
	v_lshlrev_b32_e32 v2, 16, v22
	v_and_b32_e32 v3, 0xffff0000, v22
	v_lshlrev_b32_e32 v4, 16, v23
	v_and_b32_e32 v5, 0xffff0000, v23
	s_waitcnt lgkmcnt(0)
	v_pk_mul_f32 v[2:3], v[6:7], v[2:3] op_sel_hi:[0,1]
	v_pk_mul_f32 v[4:5], v[6:7], v[4:5] op_sel_hi:[0,1]
	v_pk_mul_f32 v[2:3], v[10:11], v[2:3]
	v_pk_mul_f32 v[4:5], v[12:13], v[4:5]
	v_cvt_pk_bf16_f32 v2, v2, v3
	v_cvt_pk_bf16_f32 v3, v4, v5
	v_lshlrev_b32_e32 v4, 16, v24
	v_and_b32_e32 v5, 0xffff0000, v24
	v_lshlrev_b32_e32 v8, 16, v25
	v_and_b32_e32 v9, 0xffff0000, v25
	v_pk_mul_f32 v[4:5], v[6:7], v[4:5] op_sel_hi:[0,1]
	v_pk_mul_f32 v[6:7], v[6:7], v[8:9] op_sel_hi:[0,1]
	v_pk_mul_f32 v[4:5], v[14:15], v[4:5]
	v_pk_mul_f32 v[6:7], v[16:17], v[6:7]
	v_add_u32_e32 v18, s13, v135
	v_cvt_pk_bf16_f32 v4, v4, v5
	v_cvt_pk_bf16_f32 v5, v6, v7
	v_ashrrev_i32_e32 v19, 31, v18
	ds_write_b128 v144, v[2:5]
	v_lshlrev_b64 v[2:3], 8, v[18:19]
	v_lshl_add_u64 v[20:21], v[106:107], 0, v[2:3]
	v_mov_b32_e32 v10, 0
	v_mov_b32_e32 v14, 0
	v_mov_b32_e32 v15, 0
	v_mov_b32_e32 v16, 0
	v_mov_b32_e32 v17, 0
	s_waitcnt lgkmcnt(0)
	s_barrier
	s_and_saveexec_b64 s[16:17], s[42:43]
	s_cbranch_execz .LBB0_84
	global_load_dwordx4 v[14:17], v[20:21], off

; __device__ __forceinline__ unsigned xb_ld(unsigned* p)              { return __hip_atomic_load(p, __ATOMIC_RELAXED, __HIP_MEMORY_SCOPE_AGENT); }
; __device__ __forceinline__ void xcd_barrier_complete(unsigned* bar, unsigned x, unsigned& nloc, unsigned& nx) {
;     ...
;     for (;;) {
;         sum = 0u; cnt = 0u; mine = 0u;
; #pragma unroll
;         for (unsigned j = 0; j < 16; ++j) { const unsigned c = xb_ld(&bar[XB_XCNT(j)]); sum += c; cnt += (c > 0u) ? 1u : 0u; mine = (j == x) ? c : mine; }
;         if (sum == G) break;
;         __builtin_amdgcn_s_sleep(1);
;         if ((++sp & 255u) == 0u) { if (xb_ld(&bar[XB_TMO])) break; if (sp > XB_SPIN_CAP) { atomicAdd(&bar[XB_TMO], 1u); break; } }
.LBB0_398:
	global_load_dword v3, v1, s[74:75] sc1
	global_load_dword v0, v1, s[74:75] offset:256 sc1
	global_load_dword v2, v1, s[74:75] offset:512 sc1
	global_load_dword v4, v1, s[74:75] offset:768 sc1
	global_load_dword v5, v1, s[74:75] offset:1024 sc1
	global_load_dword v6, v1, s[74:75] offset:1280 sc1
	global_load_dword v7, v1, s[74:75] offset:1536 sc1
	global_load_dword v8, v1, s[74:75] offset:1792 sc1
	global_load_dword v9, v1, s[74:75] offset:2048 sc1
	global_load_dword v10, v1, s[74:75] offset:2304 sc1
	global_load_dword v11, v1, s[74:75] offset:2560 sc1
	global_load_dword v12, v1, s[74:75] offset:2816 sc1
	global_load_dword v13, v1, s[74:75] offset:3072 sc1
	global_load_dword v14, v1, s[74:75] offset:3328 sc1
	global_load_dword v15, v1, s[74:75] offset:3584 sc1
	global_load_dword v16, v1, s[74:75] offset:3840 sc1
	s_mov_b64 s[6:7], -1
	s_mov_b64 s[4:5], -1
	s_waitcnt vmcnt(0) lgkmcnt(0)
	v_add_u32_e32 v17, v0, v3
	v_add_u32_e32 v17, v17, v2
	v_add_u32_e32 v17, v17, v4
	v_add_u32_e32 v17, v17, v5
	v_add_u32_e32 v17, v17, v6
	v_add_u32_e32 v17, v17, v7
	v_add_u32_e32 v17, v17, v8
	v_add_u32_e32 v17, v17, v9
	v_add_u32_e32 v17, v17, v10
	v_add_u32_e32 v17, v17, v11
	v_add_u32_e32 v17, v17, v12
	v_add_u32_e32 v17, v17, v13
	v_add_u32_e32 v17, v17, v14
	v_add_u32_e32 v17, v17, v15
	v_add_u32_e32 v17, v17, v16
	v_cmp_eq_u32_e32 vcc, s68, v17
	s_cbranch_vccnz .LBB0_397
	s_and_b32 s4, s2, 0xff
	s_cmp_eq_u32 s4, 0
	s_mov_b64 s[4:5], -1
	s_mov_b64 s[8:9], -1
	s_sleep 1
	s_cbranch_scc0 .LBB0_402
	global_load_dword v17, v1, s[72:73] sc1
	s_waitcnt vmcnt(0)
	v_cmp_eq_u32_e32 vcc, 0, v17
	s_cbranch_vccnz .LBB0_404
	s_mov_b64 s[8:9], 0
